# attention tile loop: loop-carried factor move issued ahead of the loop-back barrier instead of at the head of the next segment
# baseline (speedup 1.0000x reference)
.LBB0_436:
	v_exp_f32_e32 v152, v96
	v_exp_f32_e32 v153, v97
	v_exp_f32_e32 v154, v98
	v_exp_f32_e32 v155, v99
	v_exp_f32_e32 v156, v100
	v_exp_f32_e32 v157, v101
	v_exp_f32_e32 v158, v102
	v_exp_f32_e32 v159, v103
	v_exp_f32_e32 v144, v104
	v_exp_f32_e32 v145, v105
	v_exp_f32_e32 v146, v106
	v_exp_f32_e32 v147, v107
	v_exp_f32_e32 v148, v108
	v_exp_f32_e32 v149, v109
	v_exp_f32_e32 v150, v110
	v_exp_f32_e32 v151, v111
	v_fma_f32 v80, v196, v180, v197
	v_fma_f32 v180, v80, v200, v201
	v_mov_b32_e32 v196, v199
	s_add_i32 s6, s6, 2
	s_and_b64 vcc, exec, s[4:5]
	s_waitcnt lgkmcnt(0)
	s_barrier
	s_cbranch_vccnz .LBB0_440
	s_branch .LBB0_423
